# adds: mLSTM chunk prefetch spread over the QK/QC segment (saddr loads, loop-invariant lane offsets, SGPR row bases), gate row loaded by wave 0 only, v rows by waves 0-3 only
# speedup vs baseline: 1.0087x; 1.0087x over previous
.LBB0_360:
	s_or_b64 exec, exec, s[0:1]
	s_lshl_b32 s0, s96, 2
	s_and_b32 s0, s0, 28
	s_ashr_i32 s1, s96, 5
	s_add_i32 s0, s0, s1
	s_ashr_i32 s6, s0, 2
	s_and_b32 s23, s1, 3
	s_bfe_u32 s41, s96, 0x20003
	s_add_u32 s64, s8, 0x1b36e000
	s_addc_u32 s65, s9, 0
	s_add_u32 s12, s8, 0x1f56e000
	s_addc_u32 s13, s9, 0
	s_ashr_i32 s7, s6, 31
	s_lshl_b32 s5, s41, 6
	s_ashr_i32 s40, s22, 6
	v_ashrrev_i32_e32 v3, 3, v2
	s_add_u32 s20, s8, 0xcc6e000
	v_and_b32_e32 v4, -4, v3
	s_addc_u32 s21, s9, 0
	s_lshl_b64 s[6:7], s[6:7], 11
	v_ashrrev_i32_e32 v5, 31, v4
	v_lshl_add_u64 v[4:5], s[6:7], 0, v[4:5]
	v_lshlrev_b64 v[4:5], 12, v[4:5]
	v_lshl_add_u64 v[4:5], s[64:65], 0, v[4:5]
	s_lshl_b32 s2, s23, 9
	s_waitcnt vmcnt(0)
	v_lshlrev_b32_e32 v26, 4, v2
	v_lshl_add_u64 v[4:5], v[4:5], 0, s[2:3]
	v_and_b32_e32 v158, 0x1f0, v26
	v_lshl_add_u64 v[16:17], v[4:5], 0, v[158:159]
	s_movk_i32 s10, 0x1000
	v_add_co_u32_e32 v18, vcc, s10, v16
	v_lshrrev_b32_e32 v3, 2, v2
	s_nop 0
	v_addc_co_u32_e32 v19, vcc, 0, v17, vcc
	s_movk_i32 s10, 0x2000
	v_and_or_b32 v22, v3, 62, s6
	v_mov_b32_e32 v23, s7
	v_add_co_u32_e32 v20, vcc, s10, v16
	v_lshlrev_b64 v[24:25], 11, v[22:23]
	s_nop 0
	v_addc_co_u32_e32 v21, vcc, 0, v17, vcc
	s_movk_i32 s10, 0x3000
	v_lshl_add_u64 v[24:25], s[20:21], 0, v[24:25]
	global_load_dwordx4 v[4:7], v[16:17], off
	global_load_dwordx4 v[88:91], v[16:17], off offset:2048
	global_load_dwordx4 v[8:11], v[20:21], off offset:-4096
	global_load_dwordx4 v[12:15], v[20:21], off
	global_load_dwordx4 v[92:95], v[20:21], off offset:2048
	v_add_co_u32_e32 v20, vcc, s10, v16
	v_lshl_add_u64 v[24:25], v[24:25], 0, s[2:3]
	s_lshl_b32 s36, s41, 7
	s_mov_b32 s37, s3
	v_addc_co_u32_e32 v21, vcc, 0, v17, vcc
	v_lshl_add_u64 v[24:25], v[24:25], 0, s[36:37]
	v_and_b32_e32 v158, 0x70, v26
	v_and_or_b32 v22, v2, 63, s6
	global_load_dwordx4 v[96:99], v[18:19], off offset:2048
	s_nop 0
	global_load_dwordx4 v[16:19], v[20:21], off
	v_lshl_add_u64 v[28:29], v[24:25], 0, v[158:159]
	global_load_dwordx4 v[100:103], v[20:21], off offset:2048
	global_load_dwordx4 v[24:27], v[28:29], off
	v_lshlrev_b64 v[20:21], 6, v[22:23]
	v_lshl_add_u64 v[20:21], s[12:13], 0, v[20:21]
	s_lshl_b32 s30, s23, 4
	s_mov_b32 s31, s3
	v_lshl_add_u64 v[20:21], v[20:21], 0, s[30:31]
	global_load_dwordx4 v[28:31], v[28:29], off offset:2048
	s_nop 0
	global_load_dwordx4 v[20:23], v[20:21], off
	s_lshl_b32 s4, s40, 5
	s_cmp_lt_i32 s40, 4
	s_cselect_b64 s[10:11], -1, 0
	s_cmp_lt_i32 s40, 2
	s_cselect_b64 s[34:35], -1, 0
	s_lshl_b32 s97, s40, 1
	s_add_i32 s31, s97, -8
	s_add_i32 s37, s40, 8
	v_cndmask_b32_e64 v32, 0, 1, s[34:35]
	s_cmp_gt_i32 s40, 3
	v_readfirstlane_b32 s34, v32
	s_cselect_b32 s93, 2, s34
	s_cselect_b32 s92, s31, s37
	s_add_u32 s12, s12, s30
	s_addc_u32 s13, s13, 0
	s_add_u32 s20, s20, s2
	s_addc_u32 s21, s21, 0
	s_add_u32 s30, s20, s36
	s_addc_u32 s31, s21, 0
	s_cmp_lt_u32 s22, 64
	s_cselect_b64 s[34:35], -1, 0
	s_cmp_lg_u32 s93, 0
	s_cselect_b64 s[38:39], -1, 0
	s_ashr_i32 s20, s22, 8
	s_lshl_b32 s21, s40, 4
	s_and_b32 s21, s21, 48
	s_lshl_b32 s40, s20, 4
	s_lshl_b32 s23, s23, 2
	s_add_u32 s23, s8, s23
	s_addc_u32 s37, s9, 0
	s_add_u32 s42, s23, 0x272c000
	s_addc_u32 s43, s37, 0
	s_add_u32 s8, s8, s2
	s_addc_u32 s9, s9, 0
	s_add_u32 s8, s8, s36
	s_addc_u32 s9, s9, 0
	s_add_u32 s44, s8, 0x1926e000
	s_addc_u32 s45, s9, 0
	s_cmp_eq_u32 s41, 0
	s_cselect_b64 s[8:9], -1, 0
	s_andn2_b32 s22, s22, 63
	s_add_i32 s22, s22, 0
	s_add_i32 s22, s22, 0x16500
	s_add_i32 s23, s40, 32
	s_cmp_gt_i32 s20, 3
	s_cselect_b64 s[48:49], -1, 0
	s_ashr_i32 s41, s40, 31
	s_cmp_gt_i32 s20, 1
	s_cselect_b64 s[50:51], -1, 0
	s_cmp_gt_i32 s20, -1
	s_cselect_b64 s[56:57], -1, 0
	s_add_u32 s64, s64, s2
	s_addc_u32 s65, s65, 0
	s_lshl_b32 s2, s92, 5
	s_mul_i32 s46, s92, 0x2100
	s_mov_b32 s1, 0
	s_add_i32 s2, s2, 0x14100
	s_lshl_b32 s36, s92, 6
	s_lshl_b32 s37, s92, 4
	s_add_i32 s46, s46, 0x8400
	s_waitcnt lgkmcnt(0)
	v_mov_b32_e32 v104, 0
	v_mov_b32_e32 v68, 0
	v_mov_b32_e32 v69, 0
	v_mov_b32_e32 v70, 0
	v_mov_b32_e32 v71, 0
	v_mov_b32_e32 v64, 0
	v_mov_b32_e32 v65, 0
	v_mov_b32_e32 v66, 0
	v_mov_b32_e32 v67, 0
	v_mov_b32_e32 v60, 0
	v_mov_b32_e32 v61, 0
	v_mov_b32_e32 v62, 0
	v_mov_b32_e32 v63, 0
	v_mov_b32_e32 v56, 0
	v_mov_b32_e32 v57, 0
	v_mov_b32_e32 v58, 0
	v_mov_b32_e32 v59, 0
	v_mov_b32_e32 v52, 0
	v_mov_b32_e32 v53, 0
	v_mov_b32_e32 v54, 0
	v_mov_b32_e32 v55, 0
	v_mov_b32_e32 v48, 0
	v_mov_b32_e32 v49, 0
	v_mov_b32_e32 v50, 0
	v_mov_b32_e32 v51, 0
	v_mov_b32_e32 v44, 0
	v_mov_b32_e32 v45, 0
	v_mov_b32_e32 v46, 0
	v_mov_b32_e32 v47, 0
	v_mov_b32_e32 v40, 0
	v_mov_b32_e32 v41, 0
	v_mov_b32_e32 v42, 0
	v_mov_b32_e32 v43, 0
	v_mov_b32_e32 v36, 0
	v_mov_b32_e32 v37, 0
	v_mov_b32_e32 v38, 0
	v_mov_b32_e32 v39, 0
	v_mov_b32_e32 v32, 0
	v_mov_b32_e32 v33, 0
	v_mov_b32_e32 v34, 0
	v_mov_b32_e32 v35, 0
	v_ashrrev_i32_e32 v214, 3, v2
	v_and_b32_e32 v214, -4, v214
	v_lshlrev_b32_e32 v215, 3, v2
	v_and_b32_e32 v215, 0xf8, v215
	v_lshlrev_b32_e32 v215, 1, v215
	v_lshl_add_u32 v214, v214, 12, v215
	v_add_u32_e32 v215, 0x3000, v214
	v_add_u32_e32 v214, 0x1000, v214
	v_bfe_u32 v216, v2, 3, 5
	v_and_b32_e32 v217, 7, v2
	v_lshlrev_b32_e32 v217, 4, v217
	v_lshl_add_u32 v216, v216, 12, v217
	v_and_b32_e32 v217, 63, v2
	v_lshlrev_b32_e32 v217, 6, v217
	s_add_u32 s28, s6, 64
	s_addc_u32 s29, s7, 0
	s_lshl_b64 s[18:19], s[28:29], 12
	s_add_u32 s18, s18, s64
	s_addc_u32 s19, s19, s65
	s_lshl_b64 s[26:27], s[28:29], 11
	s_add_u32 s26, s26, s30
	s_addc_u32 s27, s27, s31
	s_lshl_b64 s[28:29], s[28:29], 6
	s_add_u32 s28, s28, s12
	s_addc_u32 s29, s29, s13
	s_and_b32 s15, s34, 31
	s_cmp_eq_u32 s20, 0
	s_cselect_b32 s32, 31, 0
	s_waitcnt vmcnt(0)
.LBB0_361:
	v_mov_b32_e32 v163, v2
	s_andn2_b64 vcc, exec, s[34:35]
	v_and_b32_e32 v105, 63, v163
	s_cbranch_vccnz .LBB0_365
	v_max_f32_e32 v72, v23, v23
	v_max_f32_e32 v73, v22, v22
	v_max_f32_e32 v72, v73, v72
	ds_bpermute_b32 v74, v153, v20
	ds_bpermute_b32 v73, v153, v72
	s_waitcnt lgkmcnt(2)
	v_add_f32_e32 v75, v104, v20
	v_add_f32_e32 v72, v20, v72
	v_max_f32_e32 v76, v75, v72
	v_sub_f32_e32 v75, v75, v76
	v_mul_f32_e32 v75, 0x3fb8aa3b, v75
	s_waitcnt lgkmcnt(1)
	v_add_f32_e32 v72, v104, v74
	s_waitcnt lgkmcnt(0)
	v_add_f32_e32 v73, v74, v73
	v_lshl_add_u32 v78, v105, 2, 0
	v_exp_f32_e32 v75, v75
	v_max_f32_e32 v73, v72, v73
	v_sub_f32_e32 v77, v20, v76
	v_add_u32_e32 v79, 0x20a00, v78
	v_add_f32_e32 v74, v21, v74
	ds_write_b32 v79, v77
	v_add_u32_e32 v77, 0x20b00, v78
	v_sub_f32_e32 v74, v74, v73
	ds_write_b32 v77, v21
	v_add_u32_e32 v77, 0x20c00, v78
	v_mul_f32_e32 v74, 0x3fb8aa3b, v74
	ds_write_b32 v77, v75
	v_exp_f32_e32 v74, v74
	v_mul_f32_e32 v75, 0xbfb8aa3b, v76
	v_exp_f32_e32 v75, v75
	v_add_u32_e32 v76, 0x20d00, v78
	ds_write_b32 v76, v74
	v_add_u32_e32 v74, 0x20e00, v78
	v_cmp_eq_u32_e32 vcc, 0, v105
	ds_write_b32 v74, v75
	s_and_saveexec_b64 s[66:67], vcc
	s_cbranch_execz .LBB0_364
	v_sub_f32_e32 v72, v72, v73
	v_mul_f32_e32 v72, 0x3fb8aa3b, v72
	v_exp_f32_e32 v72, v72
	v_mov_b32_e32 v74, s89
	ds_write_b64 v74, v[72:73]

.LBB0_365:
	v_lshlrev_b32_e32 v72, 3, v163
	v_ashrrev_i32_e32 v165, 3, v163
	v_and_b32_e32 v164, 0xf8, v72
	v_and_b32_e32 v160, -4, v165
	v_lshl_add_u32 v72, v164, 1, 0
	v_mad_u64_u32 v[74:75], s[66:67], v160, s91, v[72:73]
	v_or_b32_e32 v73, 3, v165
	s_movk_i32 s47, 0x100
	s_waitcnt lgkmcnt(0)
	v_and_b32_e32 v104, 7, v163
	v_bfe_u32 v106, v163, 3, 5
	v_mad_u64_u32 v[72:73], s[66:67], v73, s91, v[72:73]
	v_cmp_gt_i32_e32 vcc, s47, v163
	ds_write_b128 v74, v[4:7]
	ds_write_b128 v74, v[88:91] offset:33792
	ds_write_b128 v74, v[8:11] offset:528
	ds_write_b128 v74, v[96:99] offset:34320
	ds_write_b128 v74, v[12:15] offset:1056
	ds_write_b128 v74, v[92:95] offset:34848
	ds_write_b128 v72, v[16:19]
	ds_write_b128 v72, v[100:103] offset:33792
	s_and_saveexec_b64 s[66:67], vcc
	s_cbranch_execz .LBB0_367
	v_mul_u32_u24_e32 v73, 0x480, v104
	v_lshlrev_b32_e32 v74, 2, v106
	v_and_b32_e32 v72, 0xffff, v24
	v_add3_u32 v73, s86, v73, v74
	v_lshrrev_b32_e32 v74, 16, v24
	v_lshl_or_b32 v72, v28, 16, v72
	v_and_or_b32 v74, v28, s94, v74
	ds_write2_b32 v73, v72, v74 offset1:36
	v_and_b32_e32 v72, 0xffff, v25
	v_lshrrev_b32_e32 v74, 16, v25
	v_lshl_or_b32 v72, v29, 16, v72
	v_and_or_b32 v74, v29, s94, v74
	ds_write2_b32 v73, v72, v74 offset0:72 offset1:108
	v_and_b32_e32 v72, 0xffff, v26
	v_lshrrev_b32_e32 v74, 16, v26
	v_lshl_or_b32 v72, v30, 16, v72
	v_and_or_b32 v74, v30, s94, v74
	ds_write2_b32 v73, v72, v74 offset0:144 offset1:180
	v_and_b32_e32 v72, 0xffff, v27
	v_lshrrev_b32_e32 v74, 16, v27
	v_lshl_or_b32 v72, v31, 16, v72
	v_and_or_b32 v74, v31, s94, v74
	ds_write2_b32 v73, v72, v74 offset0:216 offset1:252
.LBB0_367:
	s_or_b64 exec, exec, s[66:67]
	s_lshl_b32 s47, s1, 6
	s_or_b32 s47, s6, s47
	s_cmp_lg_u32 s1, 31
	s_cselect_b64 s[66:67], -1, 0
	s_cmp_eq_u32 s1, 31
.LBB0_369:
	s_waitcnt lgkmcnt(0)
	s_barrier
	s_cmp_ge_u32 s1, s15
	s_cbranch_scc1 .Lpf_skip1
	global_load_dwordx4 v[20:23], v217, s[28:29]
.Lpf_skip1:
	s_cmp_eq_u32 s1, 31
	s_cbranch_scc1 .Lpf_skip2
	global_load_dwordx4 v[4:7], v214, s[18:19] offset:-4096
	global_load_dwordx4 v[72:75], v214, s[18:19] offset:-2048
.Lpf_skip2:
	v_and_b32_e32 v161, 15, v163
	v_bfe_u32 v157, v163, 4, 2
	s_and_b64 vcc, exec, s[38:39]
	v_mul_u32_u24_e32 v155, 0x210, v161
	v_lshlrev_b32_e32 v158, 4, v157
	s_cbranch_vccz .LBB0_399
	v_lshlrev_b32_e32 v162, 4, v157
	v_add_u32_e32 v104, 0, v162
	v_lshl_add_u32 v105, v157, 3, s2
	v_add_u32_e32 v106, s36, v162
	v_lshl_add_u32 v107, v157, 2, s37
	v_add3_u32 v108, s46, v155, v162
	s_mov_b32 s68, s92
	s_mov_b32 s69, s93

.LBB0_374:
	v_or_b32_e32 v166, s21, v161
	v_mul_u32_u24_e32 v104, 0x210, v166
	v_add3_u32 v104, 0, v104, v162
	v_or_b32_e32 v167, s40, v161
	ds_read_b128 v[116:119], v104
	ds_read_b128 v[120:123], v104 offset:64
	ds_read_b128 v[124:127], v104 offset:128
	ds_read_b128 v[128:131], v104 offset:192
	ds_read_b128 v[132:135], v104 offset:256
	ds_read_b128 v[136:139], v104 offset:320
	ds_read_b128 v[140:143], v104 offset:384
	ds_read_b128 v[144:147], v104 offset:448
	v_add_u32_e32 v104, s83, v162
	v_mul_lo_u32 v105, v167, s91
	v_add_u32_e32 v168, v104, v105
	ds_read_b128 v[104:107], v168
	ds_read_b128 v[108:111], v168 offset:64
	ds_read_b128 v[112:115], v168 offset:128
	ds_read_b128 v[186:189], v168 offset:192
	ds_read_b128 v[190:193], v168 offset:256
	ds_read_b128 v[194:197], v168 offset:320
	ds_read_b128 v[198:201], v168 offset:384
	ds_read_b128 v[202:205], v168 offset:448
	s_cmp_eq_u32 s1, 31
	s_cbranch_scc1 .Lpf_skip3
	global_load_dwordx4 v[8:11], v214, s[18:19]
	global_load_dwordx4 v[76:79], v214, s[18:19] offset:2048
	global_load_dwordx4 v[12:15], v215, s[18:19] offset:-4096
	global_load_dwordx4 v[80:83], v215, s[18:19] offset:-2048
.Lpf_skip3:
	s_setprio 1
	s_waitcnt lgkmcnt(7)
	v_mfma_f32_16x16x32_bf16 v[104:107], v[104:107], v[116:119], 0
	s_mov_b32 s68, 0
	s_waitcnt lgkmcnt(6)
	v_mfma_f32_16x16x32_bf16 v[104:107], v[108:111], v[120:123], v[104:107]
	s_waitcnt lgkmcnt(5)
	v_mfma_f32_16x16x32_bf16 v[104:107], v[112:115], v[124:127], v[104:107]
	s_waitcnt lgkmcnt(4)
	v_mfma_f32_16x16x32_bf16 v[104:107], v[186:189], v[128:131], v[104:107]
	s_waitcnt lgkmcnt(3)
	v_mfma_f32_16x16x32_bf16 v[104:107], v[190:193], v[132:135], v[104:107]
	s_waitcnt lgkmcnt(2)
	v_mfma_f32_16x16x32_bf16 v[104:107], v[194:197], v[136:139], v[104:107]
	s_waitcnt lgkmcnt(1)
	v_mfma_f32_16x16x32_bf16 v[104:107], v[198:201], v[140:143], v[104:107]
	s_waitcnt lgkmcnt(0)
	v_mfma_f32_16x16x32_bf16 v[112:115], v[202:205], v[144:147], v[104:107]
	s_setprio 0
	s_nop 4
	ds_read_b128 v[104:107], v168 offset:16896
	ds_read_b128 v[108:111], v168 offset:16960
	ds_read_b128 v[186:189], v168 offset:17024
	ds_read_b128 v[190:193], v168 offset:17088
	ds_read_b128 v[194:197], v168 offset:17152
	ds_read_b128 v[198:201], v168 offset:17216
	ds_read_b128 v[202:205], v168 offset:17280
	ds_read_b128 v[206:209], v168 offset:17344
	s_cmp_eq_u32 s1, 31
	s_cbranch_scc1 .Lpf_skip4
	global_load_dwordx4 v[16:19], v215, s[18:19]
	global_load_dwordx4 v[84:87], v215, s[18:19] offset:2048
.Lpf_skip4:
	s_setprio 1
	s_waitcnt lgkmcnt(7)
	v_mfma_f32_16x16x32_bf16 v[104:107], v[104:107], v[116:119], 0
	s_waitcnt lgkmcnt(6)
	v_mfma_f32_16x16x32_bf16 v[104:107], v[108:111], v[120:123], v[104:107]
	s_waitcnt lgkmcnt(5)
	v_mfma_f32_16x16x32_bf16 v[104:107], v[186:189], v[124:127], v[104:107]
	s_waitcnt lgkmcnt(4)
	v_mfma_f32_16x16x32_bf16 v[104:107], v[190:193], v[128:131], v[104:107]
	s_waitcnt lgkmcnt(3)
	v_mfma_f32_16x16x32_bf16 v[104:107], v[194:197], v[132:135], v[104:107]
	s_waitcnt lgkmcnt(2)
	v_mfma_f32_16x16x32_bf16 v[104:107], v[198:201], v[136:139], v[104:107]
	s_waitcnt lgkmcnt(1)
	v_mfma_f32_16x16x32_bf16 v[104:107], v[202:205], v[140:143], v[104:107]
	s_waitcnt lgkmcnt(0)
	v_mfma_f32_16x16x32_bf16 v[108:111], v[206:209], v[144:147], v[104:107]
	s_setprio 0
	s_nop 4
	v_mov_b32_e32 v104, 0
	s_and_b64 vcc, exec, s[10:11]
	v_mov_b32_e32 v105, 0
	v_mov_b32_e32 v106, 0
	v_mov_b32_e32 v107, 0
	s_cbranch_vccz .LBB0_376
	ds_read_b128 v[104:107], v168 offset:33792
	ds_read_b128 v[186:189], v168 offset:33856
	ds_read_b128 v[190:193], v168 offset:33920
	ds_read_b128 v[194:197], v168 offset:33984
	ds_read_b128 v[198:201], v168 offset:34048
	ds_read_b128 v[202:205], v168 offset:34112
	ds_read_b128 v[206:209], v168 offset:34176
	ds_read_b128 v[210:213], v168 offset:34240
	s_setprio 1
	s_waitcnt lgkmcnt(7)
	v_mfma_f32_16x16x32_bf16 v[104:107], v[104:107], v[116:119], 0
	s_waitcnt lgkmcnt(6)
	v_mfma_f32_16x16x32_bf16 v[104:107], v[186:189], v[120:123], v[104:107]
	s_waitcnt lgkmcnt(5)
	v_mfma_f32_16x16x32_bf16 v[104:107], v[190:193], v[124:127], v[104:107]
	s_waitcnt lgkmcnt(4)
	v_mfma_f32_16x16x32_bf16 v[104:107], v[194:197], v[128:131], v[104:107]
	s_waitcnt lgkmcnt(3)
	v_mfma_f32_16x16x32_bf16 v[104:107], v[198:201], v[132:135], v[104:107]
	s_waitcnt lgkmcnt(2)
	v_mfma_f32_16x16x32_bf16 v[104:107], v[202:205], v[136:139], v[104:107]
	s_waitcnt lgkmcnt(1)
	v_mfma_f32_16x16x32_bf16 v[104:107], v[206:209], v[140:143], v[104:107]
	s_waitcnt lgkmcnt(0)
	v_mfma_f32_16x16x32_bf16 v[104:107], v[210:213], v[144:147], v[104:107]
	s_setprio 0
	s_mov_b32 s68, 4
.LBB0_376:
	v_lshlrev_b32_e32 v125, 2, v166
	v_add_u32_e32 v116, 0, v125
	v_add_u32_e32 v116, 0x20c00, v116
	ds_read_b32 v124, v116
	s_cmp_ge_u32 s1, s32
	s_cbranch_scc1 .Lpf_skip5
	global_load_dwordx4 v[24:27], v216, s[26:27]
	global_load_dwordx4 v[28:31], v216, s[26:27] offset:2048
.Lpf_skip5:
	v_lshl_add_u32 v116, v160, 2, 0
	s_waitcnt lgkmcnt(0)
	s_barrier
	v_add_u32_e32 v116, 0x20d00, v116
	ds_read_b128 v[116:119], v116
	v_lshrrev_b32_e32 v120, 6, v163
	v_lshrrev_b32_e32 v121, 1, v163
	v_add_lshl_u32 v120, v120, v121, 3
	v_and_b32_e32 v121, 4, v165
	v_and_or_b32 v126, v120, 56, v121
	v_lshlrev_b32_e32 v120, 16, v88
	v_lshlrev_b32_e32 v121, 16, v96
	s_waitcnt lgkmcnt(0)
	v_mul_f32_e32 v120, v116, v120
	v_mul_f32_e32 v121, v117, v121
	v_cvt_pk_bf16_f32 v120, v120, v121
	v_lshlrev_b32_e32 v121, 16, v92
	v_lshlrev_b32_e32 v122, 16, v100
	v_and_b32_e32 v88, 0xffff0000, v88
	v_mul_f32_e32 v121, v118, v121
	v_mul_f32_e32 v122, v119, v122
	v_mul_f32_e32 v88, v116, v88
	v_and_b32_e32 v96, 0xffff0000, v96
	v_cvt_pk_bf16_f32 v121, v121, v122
	v_mul_f32_e32 v96, v117, v96
	v_cvt_pk_bf16_f32 v122, v88, v96
	v_and_b32_e32 v88, 0xffff0000, v92
	v_and_b32_e32 v92, 0xffff0000, v100
	v_mul_f32_e32 v88, v118, v88
	v_mul_f32_e32 v92, v119, v92
	v_cvt_pk_bf16_f32 v123, v88, v92
	v_mul_u32_u24_e32 v88, 0x90, v164
	v_lshlrev_b32_e32 v92, 1, v126
	v_add3_u32 v88, 0, v88, v92
	v_add_u32_e32 v96, 0x8000, v88
	v_lshlrev_b32_e32 v88, 16, v89
	v_mul_f32_e32 v88, v116, v88
	v_lshlrev_b32_e32 v92, 16, v97
	ds_write2_b64 v96, v[120:121], v[122:123] offset0:128 offset1:146
	v_mul_f32_e32 v92, v117, v92
	v_cvt_pk_bf16_f32 v120, v88, v92
	v_lshlrev_b32_e32 v88, 16, v93
	v_mul_f32_e32 v88, v118, v88
	v_lshlrev_b32_e32 v92, 16, v101
	v_mul_f32_e32 v92, v119, v92
	v_cvt_pk_bf16_f32 v121, v88, v92
	v_and_b32_e32 v88, 0xffff0000, v89
	v_and_b32_e32 v89, 0xffff0000, v97
	v_mul_f32_e32 v88, v116, v88
	v_mul_f32_e32 v89, v117, v89
	v_cvt_pk_bf16_f32 v88, v88, v89
	v_and_b32_e32 v89, 0xffff0000, v93
	v_mul_f32_e32 v89, v118, v89
	v_and_b32_e32 v92, 0xffff0000, v101
	v_mul_f32_e32 v92, v119, v92
	v_cvt_pk_bf16_f32 v89, v89, v92
	ds_write2_b64 v96, v[120:121], v[88:89] offset0:164 offset1:182
	v_lshlrev_b32_e32 v88, 16, v90
	v_lshlrev_b32_e32 v89, 16, v98
	v_mul_f32_e32 v88, v116, v88
	v_mul_f32_e32 v89, v117, v89
	v_cvt_pk_bf16_f32 v88, v88, v89
	v_lshlrev_b32_e32 v89, 16, v94
	v_lshlrev_b32_e32 v92, 16, v102
	v_mul_f32_e32 v89, v118, v89
	v_mul_f32_e32 v92, v119, v92
	v_cvt_pk_bf16_f32 v89, v89, v92
	v_and_b32_e32 v90, 0xffff0000, v90
	v_and_b32_e32 v92, 0xffff0000, v98
	v_mul_f32_e32 v90, v116, v90
	v_mul_f32_e32 v92, v117, v92
	v_and_b32_e32 v93, 0xffff0000, v102
	v_cvt_pk_bf16_f32 v92, v90, v92
	v_and_b32_e32 v90, 0xffff0000, v94
	v_mul_f32_e32 v93, v119, v93
	v_mul_f32_e32 v90, v118, v90
	v_cvt_pk_bf16_f32 v93, v90, v93
	ds_write2_b64 v96, v[88:89], v[92:93] offset0:200 offset1:218
	v_lshlrev_b32_e32 v88, 16, v91
	v_lshlrev_b32_e32 v89, 16, v99
	v_mul_f32_e32 v88, v116, v88
	v_mul_f32_e32 v89, v117, v89
	v_cvt_pk_bf16_f32 v88, v88, v89
	v_lshlrev_b32_e32 v89, 16, v95
	v_lshlrev_b32_e32 v90, 16, v103
	v_mul_f32_e32 v89, v118, v89
	v_mul_f32_e32 v90, v119, v90
	v_cvt_pk_bf16_f32 v89, v89, v90
	v_and_b32_e32 v90, 0xffff0000, v91
	v_and_b32_e32 v91, 0xffff0000, v99
	v_mul_f32_e32 v90, v116, v90
	v_mul_f32_e32 v91, v117, v91
	v_cvt_pk_bf16_f32 v90, v90, v91
	v_and_b32_e32 v91, 0xffff0000, v95
	v_mul_f32_e32 v91, v118, v91
	v_and_b32_e32 v92, 0xffff0000, v103
	v_mul_f32_e32 v92, v119, v92
	v_cvt_pk_bf16_f32 v91, v91, v92
	ds_write2_b64 v96, v[88:89], v[90:91] offset0:236 offset1:254
	v_add_u32_e32 v96, s86, v158
	v_or_b32_e32 v89, s23, v161
	s_add_i32 s68, s68, s20
	v_mul_u32_u24_e32 v88, 0x90, v166
	v_mad_u64_u32 v[98:99], s[70:71], v89, s85, v[96:97]
	v_lshl_or_b32 v89, s68, 4, v161
	v_add3_u32 v88, s88, v88, v158
	v_mad_u64_u32 v[126:127], s[68:69], v89, s85, v[96:97]
	v_mad_u64_u32 v[96:97], s[68:69], v167, s85, v[96:97]
	ds_read_b128 v[92:95], v88
	ds_read_b128 v[88:91], v88 offset:64
	ds_read_b128 v[116:119], v98
	ds_read_b128 v[120:123], v98 offset:64
	ds_read_b128 v[132:135], v96 offset:64
	ds_read_b128 v[136:139], v96
	ds_read_b128 v[100:103], v126
	ds_read_b128 v[96:99], v126 offset:64
	v_pk_mul_f32 v[114:115], v[114:115], v[124:125] op_sel_hi:[1,0]
	v_pk_mul_f32 v[112:113], v[112:113], v[124:125] op_sel_hi:[1,0]
	v_cmp_eq_u32_e32 vcc, 0, v157
	v_or_b32_e32 v128, s47, v166
	s_waitcnt lgkmcnt(2)
	v_mfma_f32_16x16x32_bf16 v[112:115], v[136:139], v[92:95], v[112:115]
	v_mov_b32_e32 v129, s7
	s_add_i32 s47, 0, 0x20e00
	s_and_b64 s[68:69], s[8:9], vcc
	v_mfma_f32_16x16x32_bf16 v[112:115], v[132:135], v[88:91], v[112:115]
	v_lshl_add_u64 v[126:127], v[128:129], 4, s[42:43]
	v_add_u32_e32 v130, s47, v125
	s_mov_b64 s[70:71], -1
	s_and_b64 vcc, exec, s[48:49]
	s_cbranch_vccz .LBB0_380
	s_and_saveexec_b64 s[70:71], s[68:69]
	s_cbranch_execz .LBB0_379
	ds_read_b32 v125, v130
	v_max_f32_e64 v131, |v112|, |v112|
	s_waitcnt lgkmcnt(0)
	v_max_f32_e32 v125, v125, v125
	v_max_f32_e32 v125, v131, v125
	global_store_dword v[126:127], v125, off

.LBB0_397:
	v_mov_b32_e32 v88, s95
	ds_read_b32 v104, v88
	s_waitcnt lgkmcnt(0)
	s_barrier
	s_add_i32 s1, s1, 1
	s_cmp_eq_u32 s1, 32
	s_cbranch_scc1 .LBB0_400
	s_add_u32 s18, s18, 0x40000
	s_addc_u32 s19, s19, 0
	s_add_u32 s26, s26, 0x20000
	s_addc_u32 s27, s27, 0
	s_add_u32 s28, s28, 0x1000
	s_addc_u32 s29, s29, 0
	s_waitcnt vmcnt(0)
	v_mov_b64_e32 v[90:91], v[74:75]
	v_mov_b64_e32 v[98:99], v[78:79]
	v_mov_b64_e32 v[94:95], v[82:83]
	v_mov_b64_e32 v[102:103], v[86:87]
	v_mov_b64_e32 v[88:89], v[72:73]
	v_mov_b64_e32 v[96:97], v[76:77]
	v_mov_b64_e32 v[92:93], v[80:81]
	v_mov_b64_e32 v[100:101], v[84:85]
	s_branch .LBB0_361
